# mixer A: K rows of a unit staged once in LDS (like V) and read as fragments by ds_read_b128, instead of every wave loading its own 9 K tiles from global (4.5x fewer K requests)
# speedup vs baseline: 1.0078x; 1.0039x over previous
; #define LAS __attribute__((address_space(3)))
; __device__ __forceinline__ void seq_of(int row, int& s0, int& T) { if (row < MP) { s0 = row & ~2047; T = 2048; } else { s0 = MP + ((row - MP) & ~4095); T = 4096; } }
; __device__ __forceinline__ void a_decode(int un, int& s0, int& sh, int& r, int& n, int& u0, int& hd) {
;     const int t128 = un / 12; hd = un - t128 * 12; const int row0 = t128 * 128; int T; seq_of(row0, s0, T);
;     const int x = (row0 - s0) >> 7; sh = 2 * (hd >> 2); r = x & ((1 << sh) - 1); n = T >> sh; u0 = (x >> sh) * 128;
; }
; __device__ __forceinline__ void a_prefetch(const bf16* P, int un, int tid, int wave, int fr, int fq, v4u (&vpre)[4], bf16x8& Q0, bf16x8& Q1, bf16x8 (&K)[9][2]) {
;     int s0, sh, r, n, u0, hd; a_decode(un, s0, sh, r, n, u0, hd);
; #pragma unroll
;     for (int i = 0; i < 4; ++i) { const int e = tid + i * NTHREADS, kl = e >> 3, chunk = e & 7; int up = u0 - 64 + kl; up = up < 0 ? 0 : up; up = up > n - 1 ? n - 1 : up;
;         vpre[i] = *(const v4u*)(P + (size_t)(s0 + (up << sh) + r) * DIN + C_VA + hd * 64 + chunk * 8); }
;     { const int u = u0 + 16 * wave + fr; const bf16* qp = P + (size_t)(s0 + (u << sh) + r) * DIN + C_QA + hd * 64 + fq * 8; Q0 = *(const bf16x8*)qp; Q1 = *(const bf16x8*)(qp + 32); }
;     const int ub = u0 + 16 * wave - 64;
; #pragma unroll
;     for (int kt = 0; kt < 9; ++kt) { int up = ub + 16 * kt + fr; up = up < 0 ? 0 : up; up = up > n - 1 ? n - 1 : up;
;         const bf16* kp = P + (size_t)(s0 + (up << sh) + r) * DIN + C_KA + hd * 64 + fq * 8; K[kt][0] = *(const bf16x8*)kp; K[kt][1] = *(const bf16x8*)(kp + 32); }
; }
; __device__ __forceinline__ void mixA_mfma(const bf16* P, bf16* OG, float* LSE, LAS unsigned char* lds, int bid, int G, int tid) {
;     const int lane = tid & 63, wave = __builtin_amdgcn_readfirstlane(tid >> 6), fr = lane & 15, fq = lane >> 4;
;     LAS unsigned char* Vs = lds;
;     constexpr int NU = (M / 128) * 12;
;     constexpr float L2E = 1.4426950408889634f;
;     v4u vpre[4]; bf16x8 Qn0, Qn1, Kn[9][2];
;     if (bid < NU) a_prefetch(P, bid, tid, wave, fr, fq, vpre, Qn0, Qn1, Kn);
.LBB0_328:
.LBB0_329:
	s_cmp_lt_i32 s66, 3
	s_cselect_b64 s[20:21], -1, 0
	s_add_u32 s76, s64, 0x22500000
	s_addc_u32 s77, s65, 0
	s_add_u32 s4, s64, 0x29300000
	s_addc_u32 s5, s65, 0
	s_and_b64 s[0:1], s[20:21], s[0:1]
	v_writelane_b32 v238, s4, 29
	s_andn2_b64 vcc, exec, s[0:1]
	s_nop 0
	v_writelane_b32 v238, s5, 30
	s_cbranch_vccnz .LBB0_534
	v_and_b32_e32 v207, 15, v208
	v_readfirstlane_b32 s6, v208
	s_cmpk_gt_i32 s2, 0x8ff
	v_lshrrev_b32_e32 v137, 2, v207
	s_cbranch_scc1 .LBB0_337
	s_add_u32 s0, s64, 0x26d00000
	s_addc_u32 s1, s65, 0
	s_add_u32 s10, s64, 0x29100000
	s_mul_hi_i32 s3, s2, 0x2aaaaaab
	s_addc_u32 s11, s65, 0
	s_lshr_b32 s4, s3, 31
	s_ashr_i32 s3, s3, 1
	s_add_i32 s3, s3, s4
	s_mul_i32 s4, s3, -12
	s_add_i32 s4, s4, s2
	s_lshl_b32 s5, s3, 7
	s_cmpk_lt_i32 s2, 0x600
	s_movk_i32 s3, 0xf800
	s_cselect_b32 s7, s3, 0x7ffff000
	s_movk_i32 s12, 0x800
	s_cselect_b32 s8, s12, 0x1000
	s_and_b32 s7, s7, s5
	s_ashr_i32 s9, s4, 1
	s_sub_i32 s5, s5, s7
	s_and_b32 s14, s9, -2
	s_ashr_i32 s5, s5, 7
	s_lshl_b32 s9, -1, s14
	s_andn2_b32 s9, s5, s9
	s_ashr_i32 s5, s5, s14
	s_lshl_b32 s15, s5, 7
	v_lshrrev_b32_e32 v1, 3, v208
	v_add_u32_e32 v4, 0x200, v208
	v_add_u32_e32 v12, 0x600, v208
	s_sub_i32 s16, s15, 64
	v_lshrrev_b32_e32 v164, 3, v4
	v_or_b32_e32 v165, 0x80, v1
	v_lshrrev_b32_e32 v166, 3, v12
	s_lshr_b32 s8, s8, s14
	v_add_u32_e32 v2, s16, v1
	v_add_u32_e32 v4, s16, v164
	v_add_u32_e32 v10, s16, v165
	v_add_u32_e32 v12, s16, v166
	s_add_i32 s17, s8, -1
	v_max_i32_e32 v2, 0, v2
	v_max_i32_e32 v4, 0, v4
	v_max_i32_e32 v10, 0, v10
	v_max_i32_e32 v12, 0, v12
	v_min_i32_e32 v2, s17, v2
	v_min_i32_e32 v4, s17, v4
	v_min_i32_e32 v10, s17, v10
	v_min_i32_e32 v12, s17, v12
	s_add_i32 s18, s9, s7
	v_lshlrev_b32_e32 v2, s14, v2
	v_lshlrev_b32_e32 v4, s14, v4
	v_lshlrev_b32_e32 v10, s14, v10
	v_lshlrev_b32_e32 v12, s14, v12
	v_add_u32_e32 v2, s18, v2
	s_movk_i32 s13, 0x2c00
	v_mov_b64_e32 v[90:91], s[74:75]
	v_add_u32_e32 v4, s18, v4
	v_add_u32_e32 v10, s18, v10
	v_add_u32_e32 v12, s18, v12
	s_lshr_b32 s6, s6, 2
	v_mad_i64_i32 v[2:3], s[8:9], v2, s13, v[90:91]
	v_mad_i64_i32 v[4:5], s[8:9], v4, s13, v[90:91]
	v_mad_i64_i32 v[10:11], s[8:9], v10, s13, v[90:91]
	v_mad_i64_i32 v[12:13], s[8:9], v12, s13, v[90:91]
	s_and_b32 s22, s6, 0x3ffffff0
	s_add_i32 s8, s22, s15
	v_or_b32_e32 v18, s8, v207
	v_lshlrev_b32_e32 v18, s14, v18
	v_add_u32_e32 v18, s18, v18
	v_mad_i64_i32 v[18:19], s[6:7], v18, s13, v[90:91]
	s_sub_i32 s6, s8, 64
	s_nop 0
	v_or_b32_e32 v92, s6, v207
	v_max_i32_e32 v26, 0, v92
	v_add_u32_e32 v34, 16, v92
	v_add_u32_e32 v42, 32, v92
	v_add_u32_e32 v50, 48, v92
	v_add_u32_e32 v58, 64, v92
	v_add_u32_e32 v66, 0x50, v92
	v_add_u32_e32 v74, 0x60, v92
	v_add_u32_e32 v82, 0x70, v92
	v_add_u32_e32 v92, 0x80, v92
	v_max_i32_e32 v34, 0, v34
	v_max_i32_e32 v42, 0, v42
	v_max_i32_e32 v50, 0, v50
	v_max_i32_e32 v58, 0, v58
	v_max_i32_e32 v66, 0, v66
	v_max_i32_e32 v74, 0, v74
	v_max_i32_e32 v82, 0, v82
	v_max_i32_e32 v92, 0, v92
	s_lshl_b32 s4, s4, 6
	v_min_i32_e32 v26, s17, v26
	v_min_i32_e32 v34, s17, v34
	v_min_i32_e32 v42, s17, v42
	v_min_i32_e32 v50, s17, v50
	v_min_i32_e32 v58, s17, v58
	v_min_i32_e32 v66, s17, v66
	v_min_i32_e32 v74, s17, v74
	v_min_i32_e32 v82, s17, v82
	v_min_i32_e32 v92, s17, v92
	s_ashr_i32 s5, s4, 31
	v_lshlrev_b32_e32 v101, 3, v208
	v_lshlrev_b32_e32 v26, s14, v26
	v_lshlrev_b32_e32 v34, s14, v34
	v_lshlrev_b32_e32 v42, s14, v42
	v_lshlrev_b32_e32 v50, s14, v50
	v_lshlrev_b32_e32 v58, s14, v58
	v_lshlrev_b32_e32 v66, s14, v66
	v_lshlrev_b32_e32 v74, s14, v74
	v_lshlrev_b32_e32 v82, s14, v82
	v_lshlrev_b32_e32 v92, s14, v92
	v_and_b32_e32 v98, 56, v101
	s_lshl_b64 s[4:5], s[4:5], 1
	v_add_u32_e32 v26, s18, v26
	v_add_u32_e32 v34, s18, v34
	v_add_u32_e32 v42, s18, v42
	v_add_u32_e32 v50, s18, v50
	v_add_u32_e32 v58, s18, v58
	v_add_u32_e32 v66, s18, v66
	v_add_u32_e32 v74, s18, v74
	v_add_u32_e32 v82, s18, v82
	v_add_u32_e32 v92, s18, v92
	v_bfe_u32 v99, v208, 4, 2
	v_mov_b32_e32 v135, 0
	v_lshl_add_u64 v[2:3], v[2:3], 0, s[4:5]
	v_lshlrev_b32_e32 v134, 1, v98
	v_lshl_add_u64 v[4:5], v[4:5], 0, s[4:5]
	v_lshl_add_u64 v[10:11], v[10:11], 0, s[4:5]
	v_lshl_add_u64 v[12:13], v[12:13], 0, s[4:5]
	v_mad_i64_i32 v[26:27], s[6:7], v26, s13, v[90:91]
	v_mad_i64_i32 v[34:35], s[6:7], v34, s13, v[90:91]
	v_mad_i64_i32 v[42:43], s[6:7], v42, s13, v[90:91]
	v_mad_i64_i32 v[50:51], s[6:7], v50, s13, v[90:91]
	v_mad_i64_i32 v[58:59], s[6:7], v58, s13, v[90:91]
; __device__ __forceinline__ void a_prefetch(const bf16* P, int un, int tid, int wave, int fr, int fq, v4u (&vpre)[4], bf16x8& Q0, bf16x8& Q1, bf16x8 (&K)[9][2]) {
;     int s0, sh, r, n, u0, hd; a_decode(un, s0, sh, r, n, u0, hd);
; #pragma unroll
;     for (int i = 0; i < 4; ++i) { const int e = tid + i * NTHREADS, kl = e >> 3, chunk = e & 7; int up = u0 - 64 + kl; up = up < 0 ? 0 : up; up = up > n - 1 ? n - 1 : up;
;         vpre[i] = *(const v4u*)(P + (size_t)(s0 + (up << sh) + r) * DIN + C_VA + hd * 64 + chunk * 8); }
;     { const int u = u0 + 16 * wave + fr; const bf16* qp = P + (size_t)(s0 + (u << sh) + r) * DIN + C_QA + hd * 64 + fq * 8; Q0 = *(const bf16x8*)qp; Q1 = *(const bf16x8*)(qp + 32); }
;     const int ub = u0 + 16 * wave - 64;
; #pragma unroll
;     for (int kt = 0; kt < 9; ++kt) { int up = ub + 16 * kt + fr; up = up < 0 ? 0 : up; up = up > n - 1 ? n - 1 : up;
;         const bf16* kp = P + (size_t)(s0 + (up << sh) + r) * DIN + C_KA + hd * 64 + fq * 8; K[kt][0] = *(const bf16x8*)kp; K[kt][1] = *(const bf16x8*)(kp + 32); }
; }
; __device__ __forceinline__ void mixA_mfma(const bf16* P, bf16* OG, float* LSE, LAS unsigned char* lds, int bid, int G, int tid) {
;     ...
;         const int u = u0 + 16 * wave + fr;
;         const size_t qrow = (size_t)(s0 + (u << sh) + r);
;         f32x4 S[10];
;         const int ub = u0 + 16 * wave - 64;
; #pragma unroll
;         for (int kt = 0; kt < 9; ++kt) { f32x4 z = {0.f, 0.f, 0.f, 0.f};
;             z = __builtin_amdgcn_mfma_f32_16x16x32_bf16(Kn[kt][0], Qn0, z, 0, 0, 0);
;             S[kt] = __builtin_amdgcn_mfma_f32_16x16x32_bf16(Kn[kt][1], Qn1, z, 0, 0, 0); }
;         asm volatile("" ::: "memory");
;         if (un + G < NU) a_prefetch(P, un + G, tid, wave, fr, fq, vpre, Qn0, Qn1, Kn);
;         float mx = -1e30f;
; #pragma unroll
;         for (int kt = 0; kt < 9; ++kt)
; #pragma unroll
;             for (int t = 0; t < 4; ++t) {
;                 const int up = ub + 16 * kt + 4 * fq + t; const int rel = up > u ? up - u : u - up; const bool ok = rel <= 64 && up >= 0 && up < n;
;                 const float s = ok ? S[kt][t] * (0.125f * L2E) - slope * (float)rel : -1e30f;
;                 S[kt][t] = s; mx = fmaxf(mx, s);
;             }
;         mx = fmaxf(mx, __shfl_xor(mx, 16)); mx = fmaxf(mx, __shfl_xor(mx, 32));
;         float den = 0.f;
; #pragma unroll
;         for (int kt = 0; kt < 9; ++kt)
	v_mad_i64_i32 v[66:67], s[6:7], v66, s13, v[90:91]
	v_mad_i64_i32 v[74:75], s[6:7], v74, s13, v[90:91]
	v_mad_i64_i32 v[82:83], s[6:7], v82, s13, v[90:91]
	v_mad_i64_i32 v[90:91], s[6:7], v92, s13, v[90:91]
	v_lshl_add_u64 v[2:3], v[2:3], 0, v[134:135]
	v_lshl_add_u64 v[6:7], v[4:5], 0, v[134:135]
	v_lshl_add_u64 v[10:11], v[10:11], 0, v[134:135]
	v_lshl_add_u64 v[14:15], v[12:13], 0, v[134:135]
	v_lshl_add_u64 v[18:19], v[18:19], 0, s[4:5]
	v_lshlrev_b32_e32 v134, 4, v99
	v_lshl_add_u64 v[26:27], v[26:27], 0, s[4:5]
	v_lshl_add_u64 v[34:35], v[34:35], 0, s[4:5]
	v_lshl_add_u64 v[42:43], v[42:43], 0, s[4:5]
	v_lshl_add_u64 v[50:51], v[50:51], 0, s[4:5]
	v_lshl_add_u64 v[58:59], v[58:59], 0, s[4:5]
	v_lshl_add_u64 v[66:67], v[66:67], 0, s[4:5]
	v_lshl_add_u64 v[74:75], v[74:75], 0, s[4:5]
	v_lshl_add_u64 v[82:83], v[82:83], 0, s[4:5]
	v_lshl_add_u64 v[90:91], v[90:91], 0, s[4:5]
	v_lshl_add_u64 v[22:23], v[18:19], 0, v[134:135]
	v_lshl_add_u64 v[30:31], v[26:27], 0, v[134:135]
	v_lshl_add_u64 v[38:39], v[34:35], 0, v[134:135]
	v_lshl_add_u64 v[46:47], v[42:43], 0, v[134:135]
	v_lshl_add_u64 v[54:55], v[50:51], 0, v[134:135]
	v_lshl_add_u64 v[62:63], v[58:59], 0, v[134:135]
	v_lshl_add_u64 v[70:71], v[66:67], 0, v[134:135]
	v_lshl_add_u64 v[78:79], v[74:75], 0, v[134:135]
	v_lshl_add_u64 v[86:87], v[82:83], 0, v[134:135]
	v_lshl_add_u64 v[94:95], v[90:91], 0, v[134:135]
	v_and_b32_e32 v239, 15, v208
	v_lshrrev_b32_e32 v255, 6, v208
	v_lshl_or_b32 v239, v255, 4, v239
	v_mul_u32_u24_e32 v239, 0xa0, v239
	v_bfe_u32 v255, v208, 4, 2
	v_lshl_add_u32 v239, v255, 4, v239
	global_load_dwordx4 v[240:243], v[2:3], off offset:1536
	global_load_dwordx4 v[244:247], v[6:7], off offset:1536
	global_load_dwordx4 v[248:251], v[10:11], off offset:1536
	global_load_dwordx4 v[252:255], v[14:15], off offset:1536
	global_load_dwordx4 v[2:5], v[2:3], off offset:3072
	s_nop 0
	global_load_dwordx4 v[6:9], v[6:7], off offset:3072
	s_nop 0
	global_load_dwordx4 v[10:13], v[10:11], off offset:3072
	s_nop 0
	global_load_dwordx4 v[14:17], v[14:15], off offset:3072
	s_nop 0
	global_load_dwordx4 v[18:21], v[22:23], off
	s_nop 0
	global_load_dwordx4 v[22:25], v[22:23], off offset:64
	v_lshlrev_b32_e32 v136, 2, v99
	v_sub_u32_e32 v106, v136, v207
	v_sub_u32_e32 v107, 0, v106
	v_max_i32_e32 v106, v106, v107
	v_or_b32_e32 v168, 0xffffffc0, v136
	v_cvt_f32_u32_e32 v139, v106
	v_or_b32_e32 v169, 0xffffffd0, v136
	v_sub_u32_e32 v106, v207, v168
	s_movk_i32 s26, 0x41
	v_or_b32_e32 v170, 0xffffffe0, v136
	v_cmp_gt_u32_e64 s[6:7], s26, v106
	v_cvt_f32_ubyte0_e32 v141, v106
	v_sub_u32_e32 v106, v207, v169
	v_or_b32_e32 v171, -16, v136
	v_cvt_f32_ubyte0_e32 v143, v106
	v_sub_u32_e32 v106, v207, v170
	v_or_b32_e32 v172, 16, v136
	v_cvt_f32_ubyte0_e32 v145, v106
	v_sub_u32_e32 v106, v207, v171
	v_or_b32_e32 v173, 32, v136
	v_cvt_f32_ubyte0_e32 v147, v106
	v_sub_u32_e32 v106, v172, v207
	v_lshlrev_b32_e32 v102, 4, v208
	v_or3_b32 v103, v137, v136, s22
	s_movk_i32 s4, 0xa0
	v_or_b32_e32 v174, 48, v136
	v_cvt_f32_ubyte0_e32 v149, v106
	v_sub_u32_e32 v106, v173, v207
	v_and_b32_e32 v102, 0x70, v102
	v_mul_lo_u32 v103, v103, s4
	v_or_b32_e32 v175, 64, v136
	v_cvt_f32_ubyte0_e32 v151, v106
	v_sub_u32_e32 v106, v174, v207
	v_lshlrev_b32_e32 v100, 3, v99
	v_add_u32_e32 v102, 0, v102
	v_add_u32_e32 v103, 0, v103
	v_and_b32_e32 v101, 24, v101
	v_cmp_eq_u32_e64 s[4:5], 0, v99
	v_mul_u32_u24_e32 v99, 0xa0, v1
	v_mul_u32_u24_e32 v104, 0xa0, v164
	v_mul_u32_u24_e32 v105, 0xa0, v166
	v_cvt_f32_ubyte0_e32 v153, v106
	v_sub_u32_e32 v106, v175, v207
	v_lshlrev_b32_e32 v158, 1, v98
	v_mbcnt_lo_u32_b32 v98, -1, 0
	s_movk_i32 s23, 0x600
	v_or_b32_e32 v167, 0xffffffc0, v207
	v_cmp_gt_u32_e64 s[8:9], s26, v106
	v_cvt_f32_ubyte0_e32 v155, v106
	v_mov_b32_e32 v156, 0x3e38aa3b
	v_mov_b32_e32 v154, 0x3e38aa3b
	v_mov_b32_e32 v152, 0x3e38aa3b
	v_mov_b32_e32 v150, 0x3e38aa3b
	v_mov_b32_e32 v148, 0x3e38aa3b
	v_mov_b32_e32 v138, 0x3e38aa3b
	v_mov_b32_e32 v146, 0x3e38aa3b
	v_mov_b32_e32 v144, 0x3e38aa3b
	v_mov_b32_e32 v142, 0x3e38aa3b
	v_mov_b32_e32 v140, 0x3e38aa3b
	s_lshl_b32 s27, s68, 6
	s_lshl_b32 s29, s2, 6
	s_mov_b32 s31, 0x41400000
	s_mov_b32 s33, 0xc2fc0000
	v_add_u32_e32 v176, v102, v99
	v_add_u32_e32 v177, v102, v104
	v_add_u32_e32 v178, v102, v105
	v_lshlrev_b32_e32 v160, 1, v100
	s_mov_b32 s34, 0xf149f2ca
	v_mbcnt_hi_u32_b32 v179, -1, v98
	v_add_u32_e32 v180, v103, v101
	v_mov_b32_e32 v181, 0x42800000
	v_mov_b32_e32 v182, 0xf149f2ca
	s_mov_b32 s78, s2
	s_branch .LBB0_333

; #define LAS __attribute__((address_space(3)))
; __device__ __forceinline__ void mixA_mfma(const bf16* P, bf16* OG, float* LSE, LAS unsigned char* lds, int bid, int G, int tid) {
;     ...
;     for (int un = bid; un < NU; un += G) {
;         int s0, sh, r, n, u0, hd; a_decode(un, s0, sh, r, n, u0, hd);
;         const float slope = exp2f(-8.0f * (float)(hd + 1) / 12.0f) * (float)(1 << sh) * L2E;
;         __syncthreads();
; #pragma unroll
;         for (int i = 0; i < 4; ++i) { const int e = tid + i * NTHREADS; *(LAS v4u*)(Vs + (e >> 3) * VROW + (e & 7) * 16) = vpre[i]; }
;         __syncthreads();
;         const int u = u0 + 16 * wave + fr;
;         const size_t qrow = (size_t)(s0 + (u << sh) + r);
;         f32x4 S[10];
;         const int ub = u0 + 16 * wave - 64;
; #pragma unroll
;         for (int kt = 0; kt < 9; ++kt) { f32x4 z = {0.f, 0.f, 0.f, 0.f};
;             z = __builtin_amdgcn_mfma_f32_16x16x32_bf16(Kn[kt][0], Qn0, z, 0, 0, 0);
;             S[kt] = __builtin_amdgcn_mfma_f32_16x16x32_bf16(Kn[kt][1], Qn1, z, 0, 0, 0); }
.LBB0_333:
	s_mul_hi_i32 s14, s78, 0x2aaaaaab
	s_lshr_b32 s15, s14, 31
	s_ashr_i32 s14, s14, 1
	s_waitcnt vmcnt(0)
	s_barrier
	ds_write_b128 v176, v[2:5]
	ds_write_b128 v177, v[6:9]
	ds_write_b128 v176, v[10:13] offset:20480
	ds_write_b128 v178, v[14:17]
	ds_write_b128 v176, v[240:243] offset:40960
	ds_write_b128 v177, v[244:247] offset:40960
	ds_write_b128 v176, v[248:251] offset:61440
	ds_write_b128 v178, v[252:255] offset:40960
	s_waitcnt lgkmcnt(0)
	s_barrier
	ds_read_b128 v[26:29], v239 offset:40960
	ds_read_b128 v[30:33], v239 offset:41024
	ds_read_b128 v[34:37], v239 offset:43520
	ds_read_b128 v[38:41], v239 offset:43584
	ds_read_b128 v[42:45], v239 offset:46080
	ds_read_b128 v[46:49], v239 offset:46144
	ds_read_b128 v[50:53], v239 offset:48640
	ds_read_b128 v[54:57], v239 offset:48704
	ds_read_b128 v[58:61], v239 offset:51200
	ds_read_b128 v[62:65], v239 offset:51264
	ds_read_b128 v[66:69], v239 offset:53760
	ds_read_b128 v[70:73], v239 offset:53824
	ds_read_b128 v[74:77], v239 offset:56320
	ds_read_b128 v[78:81], v239 offset:56384
	s_waitcnt lgkmcnt(13)
	v_mfma_f32_16x16x32_bf16 v[98:101], v[26:29], v[18:21], 0
	s_add_i32 s15, s14, s15
	s_mul_i32 s14, s15, -12
	s_add_i32 s14, s78, s14
	s_add_i32 s16, s14, 1
	s_waitcnt lgkmcnt(12)
	v_mfma_f32_16x16x32_bf16 v[130:133], v[30:33], v[22:25], v[98:101]
	v_cvt_f32_i32_e32 v102, s16
	s_waitcnt lgkmcnt(11)
	v_mfma_f32_16x16x32_bf16 v[98:101], v[34:37], v[18:21], 0
	v_mul_f32_e32 v102, 0xc1000000, v102
	v_div_scale_f32 v103, s[16:17], s31, s31, v102
	s_waitcnt lgkmcnt(10)
	v_mfma_f32_16x16x32_bf16 v[126:129], v[38:41], v[22:25], v[98:101]
	v_rcp_f32_e32 v104, v103
	ds_read_b128 v[82:85], v239 offset:58880
	ds_read_b128 v[86:89], v239 offset:58944
	ds_read_b128 v[90:93], v239 offset:61440
	ds_read_b128 v[94:97], v239 offset:61504
	s_waitcnt lgkmcnt(13)
	v_mfma_f32_16x16x32_bf16 v[98:101], v[42:45], v[18:21], 0
	v_fma_f32 v105, -v103, v104, 1.0
	v_fmac_f32_e32 v104, v105, v104
	v_div_scale_f32 v105, vcc, v102, s31, v102
	s_waitcnt lgkmcnt(12)
	v_mfma_f32_16x16x32_bf16 v[122:125], v[46:49], v[22:25], v[98:101]
	v_mul_f32_e32 v106, v105, v104
	v_fma_f32 v107, -v103, v106, v105
	v_fmac_f32_e32 v106, v107, v104
	s_waitcnt lgkmcnt(11)
	v_mfma_f32_16x16x32_bf16 v[98:101], v[50:53], v[18:21], 0
	v_fma_f32 v103, -v103, v106, v105
	s_waitcnt lgkmcnt(10)
	v_mfma_f32_16x16x32_bf16 v[118:121], v[54:57], v[22:25], v[98:101]
	s_waitcnt lgkmcnt(9)
	v_mfma_f32_16x16x32_bf16 v[98:101], v[58:61], v[18:21], 0
	s_waitcnt lgkmcnt(8)
	v_mfma_f32_16x16x32_bf16 v[114:117], v[62:65], v[22:25], v[98:101]
	s_nop 6
	v_div_fmas_f32 v98, v103, v104, v106
	v_div_fixup_f32 v102, v98, s31, v102
	s_waitcnt lgkmcnt(7)
	v_mfma_f32_16x16x32_bf16 v[98:101], v[66:69], v[18:21], 0
	v_cmp_gt_f32_e32 vcc, s33, v102
	s_and_b64 s[16:17], vcc, exec
	s_cselect_b32 s16, 0xffffffc0, 0
	s_waitcnt lgkmcnt(6)
	v_mfma_f32_16x16x32_bf16 v[110:113], v[70:73], v[22:25], v[98:101]
	v_cndmask_b32_e32 v103, 0, v181, vcc
	v_add_f32_e32 v102, v102, v103
	v_exp_f32_e32 v102, v102
	s_waitcnt lgkmcnt(5)
	v_mfma_f32_16x16x32_bf16 v[98:101], v[74:77], v[18:21], 0
	s_add_i32 s35, s78, s68
	s_cmpk_gt_i32 s35, 0x8ff
	v_ldexp_f32 v134, v102, s16
	s_waitcnt lgkmcnt(4)
	v_mfma_f32_16x16x32_bf16 v[106:109], v[78:81], v[22:25], v[98:101]
	s_cselect_b64 s[16:17], -1, 0
	s_and_b64 vcc, exec, s[16:17]
	s_waitcnt lgkmcnt(3)
	v_mfma_f32_16x16x32_bf16 v[98:101], v[82:85], v[18:21], 0
	s_waitcnt lgkmcnt(2)
	v_mfma_f32_16x16x32_bf16 v[102:105], v[86:89], v[22:25], v[98:101]
	s_waitcnt lgkmcnt(1)
	v_mfma_f32_16x16x32_bf16 v[98:101], v[90:93], v[18:21], 0
	s_waitcnt lgkmcnt(0)
	v_mfma_f32_16x16x32_bf16 v[98:101], v[94:97], v[22:25], v[98:101]
	s_cbranch_vccnz .LBB0_335
; __device__ __forceinline__ void seq_of(int row, int& s0, int& T) { if (row < MP) { s0 = row & ~2047; T = 2048; } else { s0 = MP + ((row - MP) & ~4095); T = 4096; } }
; __device__ __forceinline__ void a_decode(int un, int& s0, int& sh, int& r, int& n, int& u0, int& hd) {
;     const int t128 = un / 12; hd = un - t128 * 12; const int row0 = t128 * 128; int T; seq_of(row0, s0, T);
;     const int x = (row0 - s0) >> 7; sh = 2 * (hd >> 2); r = x & ((1 << sh) - 1); n = T >> sh; u0 = (x >> sh) * 128;
; }
; __device__ __forceinline__ void a_prefetch(const bf16* P, int un, int tid, int wave, int fr, int fq, v4u (&vpre)[4], bf16x8& Q0, bf16x8& Q1, bf16x8 (&K)[9][2]) {
;     int s0, sh, r, n, u0, hd; a_decode(un, s0, sh, r, n, u0, hd);
; #pragma unroll
;     for (int i = 0; i < 4; ++i) { const int e = tid + i * NTHREADS, kl = e >> 3, chunk = e & 7; int up = u0 - 64 + kl; up = up < 0 ? 0 : up; up = up > n - 1 ? n - 1 : up;
;         vpre[i] = *(const v4u*)(P + (size_t)(s0 + (up << sh) + r) * DIN + C_VA + hd * 64 + chunk * 8); }
;     { const int u = u0 + 16 * wave + fr; const bf16* qp = P + (size_t)(s0 + (u << sh) + r) * DIN + C_QA + hd * 64 + fq * 8; Q0 = *(const bf16x8*)qp; Q1 = *(const bf16x8*)(qp + 32); }
;     const int ub = u0 + 16 * wave - 64;
; #pragma unroll
;     for (int kt = 0; kt < 9; ++kt) { int up = ub + 16 * kt + fr; up = up < 0 ? 0 : up; up = up > n - 1 ? n - 1 : up;
;         const bf16* kp = P + (size_t)(s0 + (up << sh) + r) * DIN + C_KA + hd * 64 + fq * 8; K[kt][0] = *(const bf16x8*)kp; K[kt][1] = *(const bf16x8*)(kp + 32); }
; }
; __device__ __forceinline__ void mixA_mfma(const bf16* P, bf16* OG, float* LSE, LAS unsigned char* lds, int bid, int G, int tid) {
;     ...
;         if (un + G < NU) a_prefetch(P, un + G, tid, wave, fr, fq, vpre, Qn0, Qn1, Kn);
	s_mul_hi_i32 s18, s35, 0x2aaaaaab
	s_lshr_b32 s19, s18, 31
	s_ashr_i32 s18, s18, 1
	s_add_i32 s18, s18, s19
	s_mul_i32 s19, s18, -12
	s_add_i32 s19, s35, s19
	s_lshl_b32 s24, s18, 7
	s_cmpk_lt_i32 s35, 0x600
	s_cselect_b32 s25, s3, 0x7ffff000
	s_cselect_b32 s36, s12, 0x1000
	s_and_b32 s25, s25, s24
	s_ashr_i32 s19, s19, 1
	s_sub_i32 s24, s24, s25
	s_and_b32 s37, s19, -2
	s_ashr_i32 s24, s24, 7
	s_lshl_b32 s19, -1, s37
	s_andn2_b32 s19, s24, s19
	s_ashr_i32 s24, s24, s37
	s_lshl_b32 s38, s24, 7
	s_sub_i32 s39, s38, 64
	s_add_i32 s38, s38, s22
	v_add_u32_e32 v92, s38, v167
	s_lshr_b32 s36, s36, s37
	v_add_u32_e32 v2, s39, v1
	v_add_u32_e32 v4, s39, v164
	v_add_u32_e32 v10, s39, v165
	v_add_u32_e32 v12, s39, v166
	v_max_i32_e32 v26, 0, v92
	v_add_u32_e32 v34, 16, v92
	v_add_u32_e32 v42, 32, v92
	v_add_u32_e32 v50, 48, v92
	v_add_u32_e32 v58, 64, v92
	v_add_u32_e32 v66, 0x50, v92
	v_add_u32_e32 v74, 0x60, v92
	v_add_u32_e32 v82, 0x70, v92
	v_add_u32_e32 v92, 0x80, v92
	s_add_i32 s36, s36, -1
	v_max_i32_e32 v2, 0, v2
	v_max_i32_e32 v4, 0, v4
	v_max_i32_e32 v10, 0, v10
	v_max_i32_e32 v12, 0, v12
	v_max_i32_e32 v34, 0, v34
	v_max_i32_e32 v42, 0, v42
	v_max_i32_e32 v50, 0, v50
	v_max_i32_e32 v58, 0, v58
	v_max_i32_e32 v66, 0, v66
	v_max_i32_e32 v74, 0, v74
	v_max_i32_e32 v82, 0, v82
	v_max_i32_e32 v92, 0, v92
	s_add_i32 s40, s19, s25
	s_mulk_i32 s18, 0xfd00
	s_add_i32 s19, s27, s29
	v_min_i32_e32 v2, s36, v2
	v_min_i32_e32 v4, s36, v4
	v_min_i32_e32 v10, s36, v10
	v_min_i32_e32 v12, s36, v12
	v_or_b32_e32 v18, s38, v207
	v_min_i32_e32 v26, s36, v26
	v_min_i32_e32 v34, s36, v34
	v_min_i32_e32 v42, s36, v42
	v_min_i32_e32 v50, s36, v50
	v_min_i32_e32 v58, s36, v58
	v_min_i32_e32 v66, s36, v66
	v_min_i32_e32 v74, s36, v74
	v_min_i32_e32 v82, s36, v82
	v_min_i32_e32 v92, s36, v92
	s_add_i32 s18, s19, s18
	v_lshlrev_b32_e32 v2, s37, v2
	v_lshlrev_b32_e32 v4, s37, v4
	v_lshlrev_b32_e32 v10, s37, v10
	v_lshlrev_b32_e32 v12, s37, v12
	v_lshlrev_b32_e32 v18, s37, v18
	v_lshlrev_b32_e32 v26, s37, v26
	v_lshlrev_b32_e32 v34, s37, v34
	v_lshlrev_b32_e32 v42, s37, v42
	v_lshlrev_b32_e32 v50, s37, v50
	v_lshlrev_b32_e32 v58, s37, v58
	v_lshlrev_b32_e32 v66, s37, v66
	v_lshlrev_b32_e32 v74, s37, v74
	v_lshlrev_b32_e32 v82, s37, v82
	v_lshlrev_b32_e32 v92, s37, v92
	s_ashr_i32 s19, s18, 31
	v_add_u32_e32 v2, s40, v2
	v_mov_b64_e32 v[90:91], s[74:75]
	v_add_u32_e32 v4, s40, v4
	v_add_u32_e32 v10, s40, v10
	v_add_u32_e32 v12, s40, v12
	v_add_u32_e32 v18, s40, v18
	v_add_u32_e32 v26, s40, v26
	v_add_u32_e32 v34, s40, v34
	v_add_u32_e32 v42, s40, v42
	v_add_u32_e32 v50, s40, v50
	v_add_u32_e32 v58, s40, v58
	v_add_u32_e32 v66, s40, v66
	v_add_u32_e32 v74, s40, v74
	v_add_u32_e32 v82, s40, v82
	v_add_u32_e32 v92, s40, v92
	v_mad_i64_i32 v[2:3], s[24:25], v2, s13, v[90:91]
	s_lshl_b64 s[18:19], s[18:19], 1
	v_mad_i64_i32 v[4:5], s[24:25], v4, s13, v[90:91]
	v_mad_i64_i32 v[10:11], s[24:25], v10, s13, v[90:91]
	v_mad_i64_i32 v[12:13], s[24:25], v12, s13, v[90:91]
	v_mad_i64_i32 v[18:19], s[24:25], v18, s13, v[90:91]
	v_mad_i64_i32 v[26:27], s[24:25], v26, s13, v[90:91]
	v_mad_i64_i32 v[34:35], s[24:25], v34, s13, v[90:91]
	v_mad_i64_i32 v[42:43], s[24:25], v42, s13, v[90:91]
	v_mad_i64_i32 v[50:51], s[24:25], v50, s13, v[90:91]
	v_mad_i64_i32 v[58:59], s[24:25], v58, s13, v[90:91]
	v_mad_i64_i32 v[66:67], s[24:25], v66, s13, v[90:91]
	v_mad_i64_i32 v[74:75], s[24:25], v74, s13, v[90:91]
	v_mad_i64_i32 v[82:83], s[24:25], v82, s13, v[90:91]
	v_mad_i64_i32 v[90:91], s[24:25], v92, s13, v[90:91]
	v_lshl_add_u64 v[2:3], v[2:3], 0, s[18:19]
	v_mov_b32_e32 v159, v135
	v_lshl_add_u64 v[4:5], v[4:5], 0, s[18:19]
	v_lshl_add_u64 v[10:11], v[10:11], 0, s[18:19]
	v_lshl_add_u64 v[12:13], v[12:13], 0, s[18:19]
	v_lshl_add_u64 v[18:19], v[18:19], 0, s[18:19]
	v_mov_b32_e32 v161, v135
	v_lshl_add_u64 v[26:27], v[26:27], 0, s[18:19]
	v_lshl_add_u64 v[34:35], v[34:35], 0, s[18:19]
	v_lshl_add_u64 v[42:43], v[42:43], 0, s[18:19]
	v_lshl_add_u64 v[50:51], v[50:51], 0, s[18:19]
	v_lshl_add_u64 v[58:59], v[58:59], 0, s[18:19]
	v_lshl_add_u64 v[66:67], v[66:67], 0, s[18:19]
	v_lshl_add_u64 v[74:75], v[74:75], 0, s[18:19]
	v_lshl_add_u64 v[82:83], v[82:83], 0, s[18:19]
	v_lshl_add_u64 v[90:91], v[90:91], 0, s[18:19]
	v_lshl_add_u64 v[2:3], v[2:3], 0, v[158:159]
	v_lshl_add_u64 v[6:7], v[4:5], 0, v[158:159]
	v_lshl_add_u64 v[10:11], v[10:11], 0, v[158:159]
	v_lshl_add_u64 v[14:15], v[12:13], 0, v[158:159]
	v_lshl_add_u64 v[22:23], v[18:19], 0, v[160:161]
	v_lshl_add_u64 v[30:31], v[26:27], 0, v[160:161]
	v_lshl_add_u64 v[38:39], v[34:35], 0, v[160:161]
	v_lshl_add_u64 v[46:47], v[42:43], 0, v[160:161]
	v_lshl_add_u64 v[54:55], v[50:51], 0, v[160:161]
	v_lshl_add_u64 v[62:63], v[58:59], 0, v[160:161]
	v_lshl_add_u64 v[70:71], v[66:67], 0, v[160:161]
	v_lshl_add_u64 v[78:79], v[74:75], 0, v[160:161]
	v_lshl_add_u64 v[86:87], v[82:83], 0, v[160:161]
	v_lshl_add_u64 v[94:95], v[90:91], 0, v[160:161]
	global_load_dwordx4 v[240:243], v[2:3], off offset:1536
	global_load_dwordx4 v[244:247], v[6:7], off offset:1536
	global_load_dwordx4 v[248:251], v[10:11], off offset:1536
	global_load_dwordx4 v[252:255], v[14:15], off offset:1536
	global_load_dwordx4 v[2:5], v[2:3], off offset:3072
	s_nop 0
	global_load_dwordx4 v[6:9], v[6:7], off offset:3072
	s_nop 0
	global_load_dwordx4 v[10:13], v[10:11], off offset:3072
	s_nop 0
	global_load_dwordx4 v[14:17], v[14:15], off offset:3072
	s_nop 0
	global_load_dwordx4 v[18:21], v[22:23], off
	s_nop 0
	global_load_dwordx4 v[22:25], v[22:23], off offset:64

; #define LAS __attribute__((address_space(3)))
; __device__ __forceinline__ void seq_of(int row, int& s0, int& T) { if (row < MP) { s0 = row & ~2047; T = 2048; } else { s0 = MP + ((row - MP) & ~4095); T = 4096; } }
; __device__ __forceinline__ void a_decode(int un, int& s0, int& sh, int& r, int& n, int& u0, int& hd) {
;     const int t128 = un / 12; hd = un - t128 * 12; const int row0 = t128 * 128; int T; seq_of(row0, s0, T);
;     const int x = (row0 - s0) >> 7; sh = 2 * (hd >> 2); r = x & ((1 << sh) - 1); n = T >> sh; u0 = (x >> sh) * 128;
; __device__ __forceinline__ void mixA_mfma(const bf16* P, bf16* OG, float* LSE, LAS unsigned char* lds, int bid, int G, int tid) {
;     const int lane = tid & 63, wave = __builtin_amdgcn_readfirstlane(tid >> 6), fr = lane & 15, fq = lane >> 4;
;     LAS unsigned char* Vs = lds;
;     constexpr int NU = (M / 128) * 12;
;     constexpr float L2E = 1.4426950408889634f;
;     v4u vpre[4]; bf16x8 Qn0, Qn1, Kn[9][2];
;     if (bid < NU) a_prefetch(P, bid, tid, wave, fr, fq, vpre, Qn0, Qn1, Kn);
.LBB0_1354:
	s_cmp_lt_i32 s66, 10
	s_cselect_b64 s[48:49], -1, 0
	s_add_u32 s46, s52, 0x2000
	s_addc_u32 s47, s53, 0
	s_add_u32 s3, s56, 0x40000
	s_addc_u32 s34, s57, 0
	s_add_u32 s44, s58, 0x1000
	s_addc_u32 s45, s59, 0
	v_readlane_b32 s4, v238, 13
	v_readlane_b32 s5, v238, 14
	s_add_u32 s58, s4, 0x40000
	v_readlane_b32 s6, v238, 15
	s_addc_u32 s59, s5, 0
	v_readlane_b32 s7, v238, 16
	s_add_u32 s36, s6, 0x1000
	v_readlane_b32 s8, v238, 17
	s_addc_u32 s37, s7, 0
	v_readlane_b32 s9, v238, 18
	s_add_u32 s38, s8, 0x1000
	s_addc_u32 s39, s9, 0
	s_and_b64 s[0:1], s[48:49], s[0:1]
	s_andn2_b64 vcc, exec, s[0:1]
	v_readlane_b32 s10, v238, 19
	v_readlane_b32 s11, v238, 20
	v_readlane_b32 s12, v238, 21
	v_readlane_b32 s13, v238, 22
	v_readlane_b32 s14, v238, 23
	v_readlane_b32 s15, v238, 24
	v_readlane_b32 s16, v238, 25
	v_readlane_b32 s17, v238, 26
	v_readlane_b32 s18, v238, 27
	v_readlane_b32 s19, v238, 28
	s_cbranch_vccnz .LBB0_1559
	v_and_b32_e32 v213, 15, v208
	v_readfirstlane_b32 s6, v208
	s_cmpk_gt_i32 s2, 0x8ff
	v_lshrrev_b32_e32 v137, 2, v213
	s_cbranch_scc1 .LBB0_1362
	s_add_u32 s0, s64, 0x26d00000
	s_addc_u32 s1, s65, 0
	s_add_u32 s10, s64, 0x29100000
	s_mul_hi_i32 s4, s2, 0x2aaaaaab
	s_addc_u32 s11, s65, 0
	s_lshr_b32 s5, s4, 31
	s_ashr_i32 s4, s4, 1
	s_add_i32 s4, s4, s5
	s_mul_i32 s5, s4, -12
	s_add_i32 s5, s5, s2
	s_lshl_b32 s4, s4, 7
	s_cmpk_lt_i32 s2, 0x600
	s_movk_i32 s12, 0xf800
	s_cselect_b32 s7, s12, 0x7ffff000
	s_movk_i32 s13, 0x800
	s_cselect_b32 s8, s13, 0x1000
	s_and_b32 s7, s7, s4
	s_ashr_i32 s9, s5, 1
	s_sub_i32 s4, s4, s7
	s_and_b32 s14, s9, -2
	s_ashr_i32 s4, s4, 7
	s_lshl_b32 s9, -1, s14
	s_andn2_b32 s9, s4, s9
	s_ashr_i32 s4, s4, s14
	s_lshl_b32 s15, s4, 7
	s_waitcnt vmcnt(0)
	v_lshrrev_b32_e32 v1, 3, v208
	s_waitcnt lgkmcnt(1)
	v_add_u32_e32 v4, 0x200, v208
	v_add_u32_e32 v12, 0x600, v208
	s_sub_i32 s16, s15, 64
	v_lshrrev_b32_e32 v164, 3, v4
	v_or_b32_e32 v165, 0x80, v1
	v_lshrrev_b32_e32 v166, 3, v12
	s_lshr_b32 s8, s8, s14
	v_add_u32_e32 v2, s16, v1
	v_add_u32_e32 v4, s16, v164
	v_add_u32_e32 v10, s16, v165
	v_add_u32_e32 v12, s16, v166
	s_add_i32 s17, s8, -1
	v_max_i32_e32 v2, 0, v2
	v_max_i32_e32 v4, 0, v4
	v_max_i32_e32 v10, 0, v10
	v_max_i32_e32 v12, 0, v12
	v_min_i32_e32 v2, s17, v2
	v_min_i32_e32 v4, s17, v4
	v_min_i32_e32 v10, s17, v10
	v_min_i32_e32 v12, s17, v12
	s_add_i32 s18, s9, s7
	v_lshlrev_b32_e32 v2, s14, v2
	v_lshlrev_b32_e32 v4, s14, v4
	v_lshlrev_b32_e32 v10, s14, v10
	v_lshlrev_b32_e32 v12, s14, v12
	v_add_u32_e32 v2, s18, v2
	s_movk_i32 s20, 0x2c00
	v_mov_b64_e32 v[90:91], s[74:75]
	v_add_u32_e32 v4, s18, v4
	v_add_u32_e32 v10, s18, v10
	v_add_u32_e32 v12, s18, v12
	s_lshr_b32 s6, s6, 2
	s_waitcnt lgkmcnt(0)
; __device__ __forceinline__ void a_prefetch(const bf16* P, int un, int tid, int wave, int fr, int fq, v4u (&vpre)[4], bf16x8& Q0, bf16x8& Q1, bf16x8 (&K)[9][2]) {
;     int s0, sh, r, n, u0, hd; a_decode(un, s0, sh, r, n, u0, hd);
; #pragma unroll
;     for (int i = 0; i < 4; ++i) { const int e = tid + i * NTHREADS, kl = e >> 3, chunk = e & 7; int up = u0 - 64 + kl; up = up < 0 ? 0 : up; up = up > n - 1 ? n - 1 : up;
;         vpre[i] = *(const v4u*)(P + (size_t)(s0 + (up << sh) + r) * DIN + C_VA + hd * 64 + chunk * 8); }
;     { const int u = u0 + 16 * wave + fr; const bf16* qp = P + (size_t)(s0 + (u << sh) + r) * DIN + C_QA + hd * 64 + fq * 8; Q0 = *(const bf16x8*)qp; Q1 = *(const bf16x8*)(qp + 32); }
;     const int ub = u0 + 16 * wave - 64;
; #pragma unroll
;     for (int kt = 0; kt < 9; ++kt) { int up = ub + 16 * kt + fr; up = up < 0 ? 0 : up; up = up > n - 1 ? n - 1 : up;
;         const bf16* kp = P + (size_t)(s0 + (up << sh) + r) * DIN + C_KA + hd * 64 + fq * 8; K[kt][0] = *(const bf16x8*)kp; K[kt][1] = *(const bf16x8*)(kp + 32); }
; }
; __device__ __forceinline__ void mixA_mfma(const bf16* P, bf16* OG, float* LSE, LAS unsigned char* lds, int bid, int G, int tid) {
;     ...
;         const int u = u0 + 16 * wave + fr;
;         const size_t qrow = (size_t)(s0 + (u << sh) + r);
;         f32x4 S[10];
;         const int ub = u0 + 16 * wave - 64;
; #pragma unroll
;         for (int kt = 0; kt < 9; ++kt) { f32x4 z = {0.f, 0.f, 0.f, 0.f};
;             z = __builtin_amdgcn_mfma_f32_16x16x32_bf16(Kn[kt][0], Qn0, z, 0, 0, 0);
;             S[kt] = __builtin_amdgcn_mfma_f32_16x16x32_bf16(Kn[kt][1], Qn1, z, 0, 0, 0); }
;         asm volatile("" ::: "memory");
;         if (un + G < NU) a_prefetch(P, un + G, tid, wave, fr, fq, vpre, Qn0, Qn1, Kn);
;         float mx = -1e30f;
; #pragma unroll
;         for (int kt = 0; kt < 9; ++kt)
; #pragma unroll
;             for (int t = 0; t < 4; ++t) {
;                 const int up = ub + 16 * kt + 4 * fq + t; const int rel = up > u ? up - u : u - up; const bool ok = rel <= 64 && up >= 0 && up < n;
;                 const float s = ok ? S[kt][t] * (0.125f * L2E) - slope * (float)rel : -1e30f;
;                 S[kt][t] = s; mx = fmaxf(mx, s);
;             }
;         mx = fmaxf(mx, __shfl_xor(mx, 16)); mx = fmaxf(mx, __shfl_xor(mx, 32));
;         float den = 0.f;
; #pragma unroll
;         for (int kt = 0; kt < 9; ++kt)
	v_mad_i64_i32 v[2:3], s[8:9], v2, s20, v[90:91]
	v_mad_i64_i32 v[4:5], s[8:9], v4, s20, v[90:91]
	v_mad_i64_i32 v[10:11], s[8:9], v10, s20, v[90:91]
	v_mad_i64_i32 v[12:13], s[8:9], v12, s20, v[90:91]
	s_and_b32 s21, s6, 0x3ffffff0
	s_add_i32 s8, s21, s15
	v_or_b32_e32 v18, s8, v213
	v_lshlrev_b32_e32 v18, s14, v18
	v_add_u32_e32 v18, s18, v18
	v_mad_i64_i32 v[18:19], s[6:7], v18, s20, v[90:91]
	s_sub_i32 s6, s8, 64
	s_nop 0
	v_or_b32_e32 v92, s6, v213
	v_max_i32_e32 v26, 0, v92
	v_add_u32_e32 v34, 16, v92
	v_add_u32_e32 v42, 32, v92
	v_add_u32_e32 v50, 48, v92
	v_add_u32_e32 v58, 64, v92
	v_add_u32_e32 v66, 0x50, v92
	v_add_u32_e32 v74, 0x60, v92
	v_add_u32_e32 v82, 0x70, v92
	v_add_u32_e32 v92, 0x80, v92
	v_max_i32_e32 v34, 0, v34
	v_max_i32_e32 v42, 0, v42
	v_max_i32_e32 v50, 0, v50
	v_max_i32_e32 v58, 0, v58
	v_max_i32_e32 v66, 0, v66
	v_max_i32_e32 v74, 0, v74
	v_max_i32_e32 v82, 0, v82
	v_max_i32_e32 v92, 0, v92
	s_lshl_b32 s4, s5, 6
	v_min_i32_e32 v26, s17, v26
	v_min_i32_e32 v34, s17, v34
	v_min_i32_e32 v42, s17, v42
	v_min_i32_e32 v50, s17, v50
	v_min_i32_e32 v58, s17, v58
	v_min_i32_e32 v66, s17, v66
	v_min_i32_e32 v74, s17, v74
	v_min_i32_e32 v82, s17, v82
	v_min_i32_e32 v92, s17, v92
	s_ashr_i32 s5, s4, 31
	v_lshlrev_b32_e32 v101, 3, v208
	v_lshlrev_b32_e32 v26, s14, v26
	v_lshlrev_b32_e32 v34, s14, v34
	v_lshlrev_b32_e32 v42, s14, v42
	v_lshlrev_b32_e32 v50, s14, v50
	v_lshlrev_b32_e32 v58, s14, v58
	v_lshlrev_b32_e32 v66, s14, v66
	v_lshlrev_b32_e32 v74, s14, v74
	v_lshlrev_b32_e32 v82, s14, v82
	v_lshlrev_b32_e32 v92, s14, v92
	v_and_b32_e32 v98, 56, v101
	s_lshl_b64 s[4:5], s[4:5], 1
	v_add_u32_e32 v26, s18, v26
	v_add_u32_e32 v34, s18, v34
	v_add_u32_e32 v42, s18, v42
	v_add_u32_e32 v50, s18, v50
	v_add_u32_e32 v58, s18, v58
	v_add_u32_e32 v66, s18, v66
	v_add_u32_e32 v74, s18, v74
	v_add_u32_e32 v82, s18, v82
	v_add_u32_e32 v92, s18, v92
	v_bfe_u32 v99, v208, 4, 2
	v_mov_b32_e32 v135, 0
	v_lshl_add_u64 v[2:3], v[2:3], 0, s[4:5]
	v_lshlrev_b32_e32 v134, 1, v98
	v_lshl_add_u64 v[4:5], v[4:5], 0, s[4:5]
	v_lshl_add_u64 v[10:11], v[10:11], 0, s[4:5]
	v_lshl_add_u64 v[12:13], v[12:13], 0, s[4:5]
	v_mad_i64_i32 v[26:27], s[6:7], v26, s20, v[90:91]
	v_mad_i64_i32 v[34:35], s[6:7], v34, s20, v[90:91]
	v_mad_i64_i32 v[42:43], s[6:7], v42, s20, v[90:91]
	v_mad_i64_i32 v[50:51], s[6:7], v50, s20, v[90:91]
	v_mad_i64_i32 v[58:59], s[6:7], v58, s20, v[90:91]
	v_mad_i64_i32 v[66:67], s[6:7], v66, s20, v[90:91]
	v_mad_i64_i32 v[74:75], s[6:7], v74, s20, v[90:91]
	v_mad_i64_i32 v[82:83], s[6:7], v82, s20, v[90:91]
	v_mad_i64_i32 v[90:91], s[6:7], v92, s20, v[90:91]
	v_lshl_add_u64 v[2:3], v[2:3], 0, v[134:135]
	v_lshl_add_u64 v[6:7], v[4:5], 0, v[134:135]
	v_lshl_add_u64 v[10:11], v[10:11], 0, v[134:135]
	v_lshl_add_u64 v[14:15], v[12:13], 0, v[134:135]
	v_lshl_add_u64 v[18:19], v[18:19], 0, s[4:5]
	v_lshlrev_b32_e32 v134, 4, v99
	v_lshl_add_u64 v[26:27], v[26:27], 0, s[4:5]
	v_lshl_add_u64 v[34:35], v[34:35], 0, s[4:5]
	v_lshl_add_u64 v[42:43], v[42:43], 0, s[4:5]
	v_lshl_add_u64 v[50:51], v[50:51], 0, s[4:5]
	v_lshl_add_u64 v[58:59], v[58:59], 0, s[4:5]
	v_lshl_add_u64 v[66:67], v[66:67], 0, s[4:5]
	v_lshl_add_u64 v[74:75], v[74:75], 0, s[4:5]
	v_lshl_add_u64 v[82:83], v[82:83], 0, s[4:5]
	v_lshl_add_u64 v[90:91], v[90:91], 0, s[4:5]
	v_lshl_add_u64 v[22:23], v[18:19], 0, v[134:135]
	v_lshl_add_u64 v[30:31], v[26:27], 0, v[134:135]
	v_lshl_add_u64 v[38:39], v[34:35], 0, v[134:135]
	v_lshl_add_u64 v[46:47], v[42:43], 0, v[134:135]
	v_lshl_add_u64 v[54:55], v[50:51], 0, v[134:135]
	v_lshl_add_u64 v[62:63], v[58:59], 0, v[134:135]
	v_lshl_add_u64 v[70:71], v[66:67], 0, v[134:135]
	v_lshl_add_u64 v[78:79], v[74:75], 0, v[134:135]
	v_lshl_add_u64 v[86:87], v[82:83], 0, v[134:135]
	v_lshl_add_u64 v[94:95], v[90:91], 0, v[134:135]
	v_and_b32_e32 v239, 15, v208
	v_lshrrev_b32_e32 v255, 6, v208
	v_lshl_or_b32 v239, v255, 4, v239
	v_mul_u32_u24_e32 v239, 0xa0, v239
	v_bfe_u32 v255, v208, 4, 2
	v_lshl_add_u32 v239, v255, 4, v239
	global_load_dwordx4 v[240:243], v[2:3], off offset:1536
	global_load_dwordx4 v[244:247], v[6:7], off offset:1536
	global_load_dwordx4 v[248:251], v[10:11], off offset:1536
	global_load_dwordx4 v[252:255], v[14:15], off offset:1536
	global_load_dwordx4 v[2:5], v[2:3], off offset:3072
	s_nop 0
	global_load_dwordx4 v[6:9], v[6:7], off offset:3072
	s_nop 0
	global_load_dwordx4 v[10:13], v[10:11], off offset:3072
	s_nop 0
	global_load_dwordx4 v[14:17], v[14:15], off offset:3072
	s_nop 0
	global_load_dwordx4 v[18:21], v[22:23], off
	s_nop 0
	global_load_dwordx4 v[22:25], v[22:23], off offset:64
	v_lshlrev_b32_e32 v136, 2, v99
	v_sub_u32_e32 v106, v136, v213
	v_sub_u32_e32 v107, 0, v106
	v_max_i32_e32 v106, v106, v107
	v_or_b32_e32 v168, 0xffffffc0, v136
	v_cvt_f32_u32_e32 v139, v106
	v_or_b32_e32 v169, 0xffffffd0, v136
	v_sub_u32_e32 v106, v213, v168
	s_movk_i32 s23, 0x41
	v_or_b32_e32 v170, 0xffffffe0, v136
	v_cmp_gt_u32_e64 s[6:7], s23, v106
	v_cvt_f32_ubyte0_e32 v141, v106
	v_sub_u32_e32 v106, v213, v169
	v_or_b32_e32 v171, -16, v136
	v_cvt_f32_ubyte0_e32 v143, v106
	v_sub_u32_e32 v106, v213, v170
	v_or_b32_e32 v172, 16, v136
	v_cvt_f32_ubyte0_e32 v145, v106
	v_sub_u32_e32 v106, v213, v171
	v_or_b32_e32 v173, 32, v136
	v_cvt_f32_ubyte0_e32 v147, v106
	v_sub_u32_e32 v106, v172, v213
	v_lshlrev_b32_e32 v102, 4, v208
	v_or3_b32 v103, v137, v136, s21
	s_movk_i32 s4, 0xa0
	v_or_b32_e32 v174, 48, v136
	v_cvt_f32_ubyte0_e32 v149, v106
	v_sub_u32_e32 v106, v173, v213
	v_and_b32_e32 v102, 0x70, v102
	v_mul_lo_u32 v103, v103, s4
	v_or_b32_e32 v175, 64, v136
	v_cvt_f32_ubyte0_e32 v151, v106
	v_sub_u32_e32 v106, v174, v213
	v_lshlrev_b32_e32 v100, 3, v99
	v_add_u32_e32 v102, 0, v102
	v_add_u32_e32 v103, 0, v103
	v_and_b32_e32 v101, 24, v101
	v_cmp_eq_u32_e64 s[4:5], 0, v99
	v_mul_u32_u24_e32 v99, 0xa0, v1
	v_mul_u32_u24_e32 v104, 0xa0, v164
	v_mul_u32_u24_e32 v105, 0xa0, v166
	v_cvt_f32_ubyte0_e32 v153, v106
	v_sub_u32_e32 v106, v175, v213
	v_lshlrev_b32_e32 v158, 1, v98
	v_mbcnt_lo_u32_b32 v98, -1, 0
	s_movk_i32 s22, 0x600
	v_or_b32_e32 v167, 0xffffffc0, v213
	v_cmp_gt_u32_e64 s[8:9], s23, v106
	v_cvt_f32_ubyte0_e32 v155, v106
	v_mov_b32_e32 v156, 0x3e38aa3b
	v_mov_b32_e32 v154, 0x3e38aa3b
	v_mov_b32_e32 v152, 0x3e38aa3b
	v_mov_b32_e32 v150, 0x3e38aa3b
	v_mov_b32_e32 v148, 0x3e38aa3b
	v_mov_b32_e32 v138, 0x3e38aa3b
	v_mov_b32_e32 v146, 0x3e38aa3b
	v_mov_b32_e32 v144, 0x3e38aa3b
	v_mov_b32_e32 v142, 0x3e38aa3b
	v_mov_b32_e32 v140, 0x3e38aa3b
	s_lshl_b32 s24, s68, 6
	s_lshl_b32 s25, s2, 6
	s_mov_b32 s26, 0x41400000
	s_mov_b32 s27, 0xc2fc0000
	v_add_u32_e32 v176, v102, v99
	v_add_u32_e32 v177, v102, v104
	v_add_u32_e32 v178, v102, v105
	v_lshlrev_b32_e32 v160, 1, v100
	s_mov_b32 s29, 0xf149f2ca
	v_mbcnt_hi_u32_b32 v179, -1, v98
	v_add_u32_e32 v180, v103, v101
	v_mov_b32_e32 v181, 0x42800000
	v_mov_b32_e32 v182, 0xf149f2ca
	s_mov_b32 s33, s2
	s_branch .LBB0_1358

; #define LAS __attribute__((address_space(3)))
; __device__ __forceinline__ void mixA_mfma(const bf16* P, bf16* OG, float* LSE, LAS unsigned char* lds, int bid, int G, int tid) {
;     ...
;     for (int un = bid; un < NU; un += G) {
;         int s0, sh, r, n, u0, hd; a_decode(un, s0, sh, r, n, u0, hd);
;         const float slope = exp2f(-8.0f * (float)(hd + 1) / 12.0f) * (float)(1 << sh) * L2E;
;         __syncthreads();
; #pragma unroll
;         for (int i = 0; i < 4; ++i) { const int e = tid + i * NTHREADS; *(LAS v4u*)(Vs + (e >> 3) * VROW + (e & 7) * 16) = vpre[i]; }
;         __syncthreads();
;         const int u = u0 + 16 * wave + fr;
;         const size_t qrow = (size_t)(s0 + (u << sh) + r);
;         f32x4 S[10];
;         const int ub = u0 + 16 * wave - 64;
; #pragma unroll
;         for (int kt = 0; kt < 9; ++kt) { f32x4 z = {0.f, 0.f, 0.f, 0.f};
;             z = __builtin_amdgcn_mfma_f32_16x16x32_bf16(Kn[kt][0], Qn0, z, 0, 0, 0);
;             S[kt] = __builtin_amdgcn_mfma_f32_16x16x32_bf16(Kn[kt][1], Qn1, z, 0, 0, 0); }
.LBB0_1358:
	s_mul_hi_i32 s14, s33, 0x2aaaaaab
	s_lshr_b32 s15, s14, 31
	s_ashr_i32 s14, s14, 1
	s_waitcnt vmcnt(0)
	s_barrier
	ds_write_b128 v176, v[2:5]
	ds_write_b128 v177, v[6:9]
	ds_write_b128 v176, v[10:13] offset:20480
	ds_write_b128 v178, v[14:17]
	ds_write_b128 v176, v[240:243] offset:40960
	ds_write_b128 v177, v[244:247] offset:40960
	ds_write_b128 v176, v[248:251] offset:61440
	ds_write_b128 v178, v[252:255] offset:40960
	s_waitcnt lgkmcnt(0)
	s_barrier
	ds_read_b128 v[26:29], v239 offset:40960
	ds_read_b128 v[30:33], v239 offset:41024
	ds_read_b128 v[34:37], v239 offset:43520
	ds_read_b128 v[38:41], v239 offset:43584
	ds_read_b128 v[42:45], v239 offset:46080
	ds_read_b128 v[46:49], v239 offset:46144
	ds_read_b128 v[50:53], v239 offset:48640
	ds_read_b128 v[54:57], v239 offset:48704
	ds_read_b128 v[58:61], v239 offset:51200
	ds_read_b128 v[62:65], v239 offset:51264
	ds_read_b128 v[66:69], v239 offset:53760
	ds_read_b128 v[70:73], v239 offset:53824
	ds_read_b128 v[74:77], v239 offset:56320
	ds_read_b128 v[78:81], v239 offset:56384
	s_waitcnt lgkmcnt(13)
	v_mfma_f32_16x16x32_bf16 v[98:101], v[26:29], v[18:21], 0
	s_add_i32 s15, s14, s15
	s_mul_i32 s14, s15, -12
	s_add_i32 s14, s33, s14
	s_add_i32 s16, s14, 1
	s_waitcnt lgkmcnt(12)
	v_mfma_f32_16x16x32_bf16 v[130:133], v[30:33], v[22:25], v[98:101]
	v_cvt_f32_i32_e32 v102, s16
	s_waitcnt lgkmcnt(11)
	v_mfma_f32_16x16x32_bf16 v[98:101], v[34:37], v[18:21], 0
	v_mul_f32_e32 v102, 0xc1000000, v102
	v_div_scale_f32 v103, s[16:17], s26, s26, v102
	s_waitcnt lgkmcnt(10)
	v_mfma_f32_16x16x32_bf16 v[126:129], v[38:41], v[22:25], v[98:101]
	v_rcp_f32_e32 v104, v103
	ds_read_b128 v[82:85], v239 offset:58880
	ds_read_b128 v[86:89], v239 offset:58944
	ds_read_b128 v[90:93], v239 offset:61440
	ds_read_b128 v[94:97], v239 offset:61504
	s_waitcnt lgkmcnt(13)
	v_mfma_f32_16x16x32_bf16 v[98:101], v[42:45], v[18:21], 0
	v_fma_f32 v105, -v103, v104, 1.0
	v_fmac_f32_e32 v104, v105, v104
	v_div_scale_f32 v105, vcc, v102, s26, v102
	s_waitcnt lgkmcnt(12)
	v_mfma_f32_16x16x32_bf16 v[122:125], v[46:49], v[22:25], v[98:101]
	v_mul_f32_e32 v106, v105, v104
	v_fma_f32 v107, -v103, v106, v105
	v_fmac_f32_e32 v106, v107, v104
	s_waitcnt lgkmcnt(11)
	v_mfma_f32_16x16x32_bf16 v[98:101], v[50:53], v[18:21], 0
	v_fma_f32 v103, -v103, v106, v105
	s_waitcnt lgkmcnt(10)
	v_mfma_f32_16x16x32_bf16 v[118:121], v[54:57], v[22:25], v[98:101]
	s_waitcnt lgkmcnt(9)
	v_mfma_f32_16x16x32_bf16 v[98:101], v[58:61], v[18:21], 0
	s_waitcnt lgkmcnt(8)
	v_mfma_f32_16x16x32_bf16 v[114:117], v[62:65], v[22:25], v[98:101]
	s_nop 5
	v_div_fmas_f32 v98, v103, v104, v106
	v_div_fixup_f32 v102, v98, s26, v102
	s_waitcnt lgkmcnt(7)
	v_mfma_f32_16x16x32_bf16 v[98:101], v[66:69], v[18:21], 0
	v_cmp_gt_f32_e32 vcc, s27, v102
	s_and_b64 s[16:17], vcc, exec
	s_cselect_b32 s16, 0xffffffc0, 0
	s_waitcnt lgkmcnt(6)
	v_mfma_f32_16x16x32_bf16 v[110:113], v[70:73], v[22:25], v[98:101]
	v_cndmask_b32_e32 v103, 0, v181, vcc
	v_add_f32_e32 v102, v102, v103
	v_exp_f32_e32 v102, v102
	s_waitcnt lgkmcnt(5)
	v_mfma_f32_16x16x32_bf16 v[98:101], v[74:77], v[18:21], 0
	s_add_i32 s31, s33, s68
	s_cmpk_gt_i32 s31, 0x8ff
	v_ldexp_f32 v134, v102, s16
	s_waitcnt lgkmcnt(4)
	v_mfma_f32_16x16x32_bf16 v[106:109], v[78:81], v[22:25], v[98:101]
	s_cselect_b64 s[16:17], -1, 0
	s_and_b64 vcc, exec, s[16:17]
	s_waitcnt lgkmcnt(3)
	v_mfma_f32_16x16x32_bf16 v[98:101], v[82:85], v[18:21], 0
	s_waitcnt lgkmcnt(2)
	v_mfma_f32_16x16x32_bf16 v[102:105], v[86:89], v[22:25], v[98:101]
	s_waitcnt lgkmcnt(1)
	v_mfma_f32_16x16x32_bf16 v[98:101], v[90:93], v[18:21], 0
	s_waitcnt lgkmcnt(0)
	v_mfma_f32_16x16x32_bf16 v[98:101], v[94:97], v[22:25], v[98:101]
	s_cbranch_vccnz .LBB0_1360
; __device__ __forceinline__ void seq_of(int row, int& s0, int& T) { if (row < MP) { s0 = row & ~2047; T = 2048; } else { s0 = MP + ((row - MP) & ~4095); T = 4096; } }
; __device__ __forceinline__ void a_decode(int un, int& s0, int& sh, int& r, int& n, int& u0, int& hd) {
;     const int t128 = un / 12; hd = un - t128 * 12; const int row0 = t128 * 128; int T; seq_of(row0, s0, T);
;     const int x = (row0 - s0) >> 7; sh = 2 * (hd >> 2); r = x & ((1 << sh) - 1); n = T >> sh; u0 = (x >> sh) * 128;
; }
; __device__ __forceinline__ void a_prefetch(const bf16* P, int un, int tid, int wave, int fr, int fq, v4u (&vpre)[4], bf16x8& Q0, bf16x8& Q1, bf16x8 (&K)[9][2]) {
;     int s0, sh, r, n, u0, hd; a_decode(un, s0, sh, r, n, u0, hd);
; #pragma unroll
;     for (int i = 0; i < 4; ++i) { const int e = tid + i * NTHREADS, kl = e >> 3, chunk = e & 7; int up = u0 - 64 + kl; up = up < 0 ? 0 : up; up = up > n - 1 ? n - 1 : up;
;         vpre[i] = *(const v4u*)(P + (size_t)(s0 + (up << sh) + r) * DIN + C_VA + hd * 64 + chunk * 8); }
;     { const int u = u0 + 16 * wave + fr; const bf16* qp = P + (size_t)(s0 + (u << sh) + r) * DIN + C_QA + hd * 64 + fq * 8; Q0 = *(const bf16x8*)qp; Q1 = *(const bf16x8*)(qp + 32); }
;     const int ub = u0 + 16 * wave - 64;
; #pragma unroll
;     for (int kt = 0; kt < 9; ++kt) { int up = ub + 16 * kt + fr; up = up < 0 ? 0 : up; up = up > n - 1 ? n - 1 : up;
;         const bf16* kp = P + (size_t)(s0 + (up << sh) + r) * DIN + C_KA + hd * 64 + fq * 8; K[kt][0] = *(const bf16x8*)kp; K[kt][1] = *(const bf16x8*)(kp + 32); }
; }
; __device__ __forceinline__ void mixA_mfma(const bf16* P, bf16* OG, float* LSE, LAS unsigned char* lds, int bid, int G, int tid) {
;     ...
;         if (un + G < NU) a_prefetch(P, un + G, tid, wave, fr, fq, vpre, Qn0, Qn1, Kn);
	s_mul_hi_i32 s18, s31, 0x2aaaaaab
	s_lshr_b32 s19, s18, 31
	s_ashr_i32 s18, s18, 1
	s_add_i32 s18, s18, s19
	s_mul_i32 s19, s18, -12
	s_add_i32 s19, s31, s19
	s_lshl_b32 s35, s18, 7
	s_cmpk_lt_i32 s31, 0x600
	s_cselect_b32 s40, s12, 0x7ffff000
	s_cselect_b32 s41, s13, 0x1000
	s_and_b32 s40, s40, s35
	s_ashr_i32 s19, s19, 1
	s_sub_i32 s35, s35, s40
	s_and_b32 s42, s19, -2
	s_ashr_i32 s35, s35, 7
	s_lshl_b32 s19, -1, s42
	s_andn2_b32 s19, s35, s19
	s_ashr_i32 s35, s35, s42
	s_lshl_b32 s35, s35, 7
	s_sub_i32 s43, s35, 64
	s_add_i32 s35, s35, s21
	v_add_u32_e32 v92, s35, v167
	s_lshr_b32 s41, s41, s42
	v_add_u32_e32 v2, s43, v1
	v_add_u32_e32 v4, s43, v164
	v_add_u32_e32 v10, s43, v165
	v_add_u32_e32 v12, s43, v166
	v_max_i32_e32 v26, 0, v92
	v_add_u32_e32 v34, 16, v92
	v_add_u32_e32 v42, 32, v92
	v_add_u32_e32 v50, 48, v92
	v_add_u32_e32 v58, 64, v92
	v_add_u32_e32 v66, 0x50, v92
	v_add_u32_e32 v74, 0x60, v92
	v_add_u32_e32 v82, 0x70, v92
	v_add_u32_e32 v92, 0x80, v92
	s_add_i32 s50, s41, -1
	v_max_i32_e32 v2, 0, v2
	v_max_i32_e32 v4, 0, v4
	v_max_i32_e32 v10, 0, v10
	v_max_i32_e32 v12, 0, v12
	v_max_i32_e32 v34, 0, v34
	v_max_i32_e32 v42, 0, v42
	v_max_i32_e32 v50, 0, v50
	v_max_i32_e32 v58, 0, v58
	v_max_i32_e32 v66, 0, v66
	v_max_i32_e32 v74, 0, v74
	v_max_i32_e32 v82, 0, v82
	v_max_i32_e32 v92, 0, v92
	s_add_i32 s51, s19, s40
	s_mulk_i32 s18, 0xfd00
	s_add_i32 s19, s24, s25
	v_min_i32_e32 v2, s50, v2
	v_min_i32_e32 v4, s50, v4
	v_min_i32_e32 v10, s50, v10
	v_min_i32_e32 v12, s50, v12
	v_or_b32_e32 v18, s35, v213
	v_min_i32_e32 v26, s50, v26
	v_min_i32_e32 v34, s50, v34
	v_min_i32_e32 v42, s50, v42
	v_min_i32_e32 v50, s50, v50
	v_min_i32_e32 v58, s50, v58
	v_min_i32_e32 v66, s50, v66
	v_min_i32_e32 v74, s50, v74
	v_min_i32_e32 v82, s50, v82
	v_min_i32_e32 v92, s50, v92
	s_add_i32 s18, s19, s18
	v_lshlrev_b32_e32 v2, s42, v2
	v_lshlrev_b32_e32 v4, s42, v4
	v_lshlrev_b32_e32 v10, s42, v10
	v_lshlrev_b32_e32 v12, s42, v12
	v_lshlrev_b32_e32 v18, s42, v18
	v_lshlrev_b32_e32 v26, s42, v26
	v_lshlrev_b32_e32 v34, s42, v34
	v_lshlrev_b32_e32 v42, s42, v42
	v_lshlrev_b32_e32 v50, s42, v50
	v_lshlrev_b32_e32 v58, s42, v58
	v_lshlrev_b32_e32 v66, s42, v66
	v_lshlrev_b32_e32 v74, s42, v74
	v_lshlrev_b32_e32 v82, s42, v82
	v_lshlrev_b32_e32 v92, s42, v92
	s_ashr_i32 s19, s18, 31
	v_add_u32_e32 v2, s51, v2
	v_mov_b64_e32 v[90:91], s[74:75]
	v_add_u32_e32 v4, s51, v4
	v_add_u32_e32 v10, s51, v10
	v_add_u32_e32 v12, s51, v12
	v_add_u32_e32 v18, s51, v18
	v_add_u32_e32 v26, s51, v26
	v_add_u32_e32 v34, s51, v34
	v_add_u32_e32 v42, s51, v42
	v_add_u32_e32 v50, s51, v50
	v_add_u32_e32 v58, s51, v58
	v_add_u32_e32 v66, s51, v66
	v_add_u32_e32 v74, s51, v74
	v_add_u32_e32 v82, s51, v82
	v_add_u32_e32 v92, s51, v92
	v_mad_i64_i32 v[2:3], s[40:41], v2, s20, v[90:91]
	s_lshl_b64 s[18:19], s[18:19], 1
	v_mad_i64_i32 v[4:5], s[40:41], v4, s20, v[90:91]
	v_mad_i64_i32 v[10:11], s[40:41], v10, s20, v[90:91]
	v_mad_i64_i32 v[12:13], s[40:41], v12, s20, v[90:91]
	v_mad_i64_i32 v[18:19], s[40:41], v18, s20, v[90:91]
	v_mad_i64_i32 v[26:27], s[40:41], v26, s20, v[90:91]
	v_mad_i64_i32 v[34:35], s[40:41], v34, s20, v[90:91]
	v_mad_i64_i32 v[42:43], s[40:41], v42, s20, v[90:91]
	v_mad_i64_i32 v[50:51], s[40:41], v50, s20, v[90:91]
	v_mad_i64_i32 v[58:59], s[40:41], v58, s20, v[90:91]
	v_mad_i64_i32 v[66:67], s[40:41], v66, s20, v[90:91]
	v_mad_i64_i32 v[74:75], s[40:41], v74, s20, v[90:91]
	v_mad_i64_i32 v[82:83], s[40:41], v82, s20, v[90:91]
	v_mad_i64_i32 v[90:91], s[40:41], v92, s20, v[90:91]
	v_lshl_add_u64 v[2:3], v[2:3], 0, s[18:19]
	v_mov_b32_e32 v159, v135
	v_lshl_add_u64 v[4:5], v[4:5], 0, s[18:19]
	v_lshl_add_u64 v[10:11], v[10:11], 0, s[18:19]
	v_lshl_add_u64 v[12:13], v[12:13], 0, s[18:19]
	v_lshl_add_u64 v[18:19], v[18:19], 0, s[18:19]
	v_mov_b32_e32 v161, v135
	v_lshl_add_u64 v[26:27], v[26:27], 0, s[18:19]
	v_lshl_add_u64 v[34:35], v[34:35], 0, s[18:19]
	v_lshl_add_u64 v[42:43], v[42:43], 0, s[18:19]
	v_lshl_add_u64 v[50:51], v[50:51], 0, s[18:19]
	v_lshl_add_u64 v[58:59], v[58:59], 0, s[18:19]
	v_lshl_add_u64 v[66:67], v[66:67], 0, s[18:19]
	v_lshl_add_u64 v[74:75], v[74:75], 0, s[18:19]
	v_lshl_add_u64 v[82:83], v[82:83], 0, s[18:19]
	v_lshl_add_u64 v[90:91], v[90:91], 0, s[18:19]
	v_lshl_add_u64 v[2:3], v[2:3], 0, v[158:159]
	v_lshl_add_u64 v[6:7], v[4:5], 0, v[158:159]
	v_lshl_add_u64 v[10:11], v[10:11], 0, v[158:159]
	v_lshl_add_u64 v[14:15], v[12:13], 0, v[158:159]
	v_lshl_add_u64 v[22:23], v[18:19], 0, v[160:161]
	v_lshl_add_u64 v[30:31], v[26:27], 0, v[160:161]
	v_lshl_add_u64 v[38:39], v[34:35], 0, v[160:161]
	v_lshl_add_u64 v[46:47], v[42:43], 0, v[160:161]
	v_lshl_add_u64 v[54:55], v[50:51], 0, v[160:161]
	v_lshl_add_u64 v[62:63], v[58:59], 0, v[160:161]
	v_lshl_add_u64 v[70:71], v[66:67], 0, v[160:161]
	v_lshl_add_u64 v[78:79], v[74:75], 0, v[160:161]
	v_lshl_add_u64 v[86:87], v[82:83], 0, v[160:161]
	v_lshl_add_u64 v[94:95], v[90:91], 0, v[160:161]
	global_load_dwordx4 v[240:243], v[2:3], off offset:1536
	global_load_dwordx4 v[244:247], v[6:7], off offset:1536
	global_load_dwordx4 v[248:251], v[10:11], off offset:1536
	global_load_dwordx4 v[252:255], v[14:15], off offset:1536
	global_load_dwordx4 v[2:5], v[2:3], off offset:3072
	s_nop 0
	global_load_dwordx4 v[6:9], v[6:7], off offset:3072
	s_nop 0
	global_load_dwordx4 v[10:13], v[10:11], off offset:3072
	s_nop 0
	global_load_dwordx4 v[14:17], v[14:15], off offset:3072
	s_nop 0
	global_load_dwordx4 v[18:21], v[22:23], off
	s_nop 0
	global_load_dwordx4 v[22:25], v[22:23], off offset:64
